# v72 + kernarg s_loads issued together at entry + write-through (sc1) for the P4 prologue's final-output stores (h state, LN(v) sample rows)
# speedup vs baseline: 1.0008x; 1.0008x over previous
; __device__ __forceinline__ float bf_lo(unsigned w) { return __uint_as_float(w << 16); }
; __device__ __forceinline__ unsigned pk4f8(float a, float b, float c, float d) { int p = __builtin_amdgcn_cvt_pk_fp8_f32(sat8(a), sat8(b), 0, false); p = __builtin_amdgcn_cvt_pk_fp8_f32(sat8(c), sat8(d), p, true); return (unsigned)p; }
; __device__ __forceinline__ float bf_hi(unsigned w) { return __uint_as_float(w & 0xffff0000u); }
; __device__ __forceinline__ float ld_agent_f32(const float* p) { return __uint_as_float(__hip_atomic_load((const unsigned*)p, RLX_AGENT)); }
; __device__ __forceinline__ void p4_mixers(const Args& a, const Ctx& C) {
;     ...
;     if (C.wave >= 2) for (int i = C.vcu * 384 + (C.tid - 128); i < DEC * DA / 4; i += C.G * 384) { const int r = i >> 8, c4 = (i & 255) * 4, hd = c4 >> 7; const size_t row = (size_t)NBATCH * SEQ + r;
;         const float s1 = ld_agent_f32(VST + 2 * row), s2 = ld_agent_f32(VST + 2 * row + 1);
;         const float mu = s1 * (1.0f / DA), var = s2 * (1.0f / DA) - mu * mu, rs = __builtin_amdgcn_rsqf(var + EPS);
;         const v2u vq = *(const v2u*)(PROJ + row * DIN + DA + c4), uq = *(const v2u*)(PROJ + row * DIN + c4);
;         const f32x4 lg = *(const f32x4*)(a.in[I_LNG] + c4), lb = *(const f32x4*)(a.in[I_LNB] + c4);
;         const f32x4 vf = (f32x4){bf_lo(vq.x), bf_hi(vq.x), bf_lo(vq.y), bf_hi(vq.y)}, uf = (f32x4){bf_lo(uq.x), bf_hi(uq.x), bf_lo(uq.y), bf_hi(uq.y)};
;         const f32x4 ln = (vf - mu) * rs * lg + lb;
;         *(f32x4*)(a.out + OUT_VS + (size_t)r * DA + c4) = ln;
;         const float w00 = a.in[I_WS][(size_t)hd * 128 * 128], bs0 = a.in[I_BS][hd * 128];
;         const f32x4 o = uf * (ln * w00 + bs0);
;         *(unsigned*)((unsigned char*)Y + row * DM + c4) = pk4f8(o[0], o[1], o[2], o[3]); }
.LBB0_958:
	v_ashrrev_i32_e32 v18, 8, v6
	v_ashrrev_i32_e32 v19, 31, v18
	v_lshl_add_u64 v[22:23], v[18:19], 0, s[24:25]
	v_lshl_add_u64 v[12:13], v[22:23], 3, s[4:5]
	global_load_dword v25, v[12:13], off sc1
	global_load_dword v24, v[12:13], off offset:4 sc1
	v_and_b32_e32 v4, 0x3fc, v8
	v_mov_b32_e32 v11, v5
	v_lshlrev_b32_e32 v10, 1, v4
	v_lshlrev_b32_e32 v20, 2, v4
	v_mad_i64_i32 v[14:15], s[30:31], v22, s27, v[2:3]
	v_lshl_add_u64 v[26:27], v[14:15], 0, v[10:11]
	global_load_dwordx4 v[10:13], v20, s[16:17]
	global_load_dwordx2 v[28:29], v[26:27], off offset:2048
	global_load_dwordx4 v[14:17], v20, s[18:19]
	v_lshlrev_b64 v[18:19], 12, v[18:19]
	v_mov_b32_e32 v21, v5
	v_lshl_add_u64 v[18:19], s[10:11], 0, v[18:19]
	v_lshl_add_u64 v[18:19], v[18:19], 0, v[20:21]
	global_load_dwordx2 v[20:21], v[26:27], off
	v_and_b32_e32 v31, 0x1c000, v7
	v_and_b32_e32 v30, 0x380, v8
	v_lshlrev_b32_e32 v31, 2, v31
	v_lshlrev_b32_e32 v30, 2, v30
	v_add_u32_e32 v6, s0, v6
	v_cmp_lt_i32_e32 vcc, s29, v6
	v_add_u32_e32 v7, s1, v7
	v_add_u32_e32 v8, s2, v8
	s_or_b64 s[14:15], vcc, s[14:15]
	s_waitcnt vmcnt(4)
	v_pk_mul_f32 v[24:25], v[24:25], s[26:27] op_sel_hi:[1,0]
	s_nop 0
	v_fma_f32 v24, -v25, v25, v24
	v_add_f32_e32 v24, 0x358637bd, v24
	v_rsq_f32_e32 v24, v24
	s_waitcnt vmcnt(2)
	v_lshlrev_b32_e32 v32, 16, v28
	v_and_b32_e32 v28, 0xffff0000, v28
	v_lshlrev_b32_e32 v26, 16, v29
	v_and_b32_e32 v27, 0xffff0000, v29
	v_sub_f32_e32 v27, v27, v25
	v_sub_f32_e32 v26, v26, v25
	v_sub_f32_e32 v29, v28, v25
	v_sub_f32_e32 v28, v32, v25
	v_pk_mul_f32 v[28:29], v[24:25], v[28:29] op_sel_hi:[0,1]
	v_pk_mul_f32 v[24:25], v[24:25], v[26:27] op_sel_hi:[0,1]
	s_waitcnt vmcnt(1)
	v_pk_fma_f32 v[12:13], v[12:13], v[24:25], v[16:17]
	v_pk_fma_f32 v[10:11], v[10:11], v[28:29], v[14:15]
	global_store_dwordx4 v[18:19], v[10:13], off sc1
	global_load_dword v14, v31, s[20:21]
	global_load_dword v16, v30, s[22:23]
	v_mov_b32_e32 v15, v5
	s_waitcnt vmcnt(3)
	v_lshlrev_b32_e32 v18, 16, v20
	v_and_b32_e32 v19, 0xffff0000, v20
	v_lshlrev_b32_e32 v20, 16, v21
	v_and_b32_e32 v21, 0xffff0000, v21
	s_waitcnt vmcnt(0)
	v_pk_fma_f32 v[10:11], v[14:15], v[10:11], v[16:17] op_sel_hi:[0,1,0]
	v_pk_mul_f32 v[10:11], v[10:11], v[18:19]
	v_pk_fma_f32 v[12:13], v[14:15], v[12:13], v[16:17] op_sel_hi:[0,1,0]
	v_med3_f32 v10, v10, s28, v9
	v_med3_f32 v11, v11, s28, v9
	v_cvt_pk_fp8_f32 v15, v10, v11
	v_pk_mul_f32 v[10:11], v[12:13], v[20:21]
	s_nop 0
	v_med3_f32 v10, v10, s28, v9
	v_med3_f32 v11, v11, s28, v9
	v_cvt_pk_fp8_f32 v15, v10, v11 op_sel:[0,0,1]
	v_lshlrev_b64 v[10:11], 11, v[22:23]
	v_lshl_add_u64 v[10:11], s[70:71], 0, v[10:11]
	v_lshl_add_u64 v[10:11], v[10:11], 0, v[4:5]
	global_store_dword v[10:11], v15, off
	s_andn2_b64 exec, exec, s[14:15]
	s_cbranch_execnz .LBB0_958

; __device__ __forceinline__ void s5_load_consts(S5C& K, const Args& a, int g, int lane) {
;     const int fr = lane & 15, q = lane >> 4;
;     const float* ABAR = (const float*)(a.ws + WS_S5C + S5C_ABAR) + (size_t)g * 128;
;     const bf16* BBAR = (const bf16*)(a.ws + WS_S5C + S5C_BBAR) + (size_t)g * 2048;
; #pragma unroll
;     for (int j = 0; j < 4; ++j) { const f32x4 x0 = *(const f32x4*)(ABAR + 2 * (16 * j + 4 * q)), x1 = *(const f32x4*)(ABAR + 2 * (16 * j + 4 * q) + 4);
;         K.ar[j] = (f32x4){x0[0], x0[2], x1[0], x1[2]}; K.ai[j] = (f32x4){x0[1], x0[3], x1[1], x1[3]}; }
; #pragma unroll
;     for (int mt = 0; mt < 8; ++mt) K.Bf[mt] = *(const v2u*)(BBAR + (mt * 16 + fr) * 16 + 4 * q);
;     const float* cre = a.in[I_CRE] + ((size_t)g * 16 + fr) * 64; const float* cim = a.in[I_CIM] + ((size_t)g * 16 + fr) * 64;
; #pragma unroll
;     for (int j = 0; j < 4; ++j) { const f32x4 r4 = *(const f32x4*)(cre + 16 * j + 4 * q), i4 = *(const f32x4*)(cim + 16 * j + 4 * q); K.Cf[j] = pack8(r4, -i4); }
;     const float* wg = a.in[I_WGLU] + (size_t)g * 512;
;     { f32x4 v, gt;
; #pragma unroll
;       for (int e = 0; e < 4; ++e) { v[e] = wg[(4 * q + e) * 32 + fr]; gt[e] = wg[(4 * q + e) * 32 + 16 + fr]; }
;       K.Wv = (v2u){pk2(v[0], v[1]), pk2(v[2], v[3])}; K.Wg = (v2u){pk2(gt[0], gt[1]), pk2(gt[2], gt[3])}; }
;     K.dsk = *(const f32x4*)(a.in[I_DSKIP] + g * 16 + 4 * q);
;     K.bv = *(const f32x4*)(a.in[I_BGLU] + g * 32 + 4 * q); K.bg = *(const f32x4*)(a.in[I_BGLU] + g * 32 + 16 + 4 * q);
; __device__ __forceinline__ void s5_sample_task(const Args& a, int rb, int g, int lane) {
;     const bf16* PROJ = (const bf16*)(a.ws + WS_PROJ); bf16* Y = (bf16*)(a.ws + WS_Y);
;     const int n = lane & 15, q = lane >> 4, i = 16 * rb + n; const size_t row = (size_t)NBATCH * SEQ + i;
;     S5C K; s5_load_consts(K, a, g, lane);
;     f32x4 hre[4], him[4];
;     const float* sre = a.in[I_SRE] + ((size_t)i * NG + g) * PST; const float* sim = a.in[I_SIM] + ((size_t)i * NG + g) * PST;
; #pragma unroll
;     for (int j = 0; j < 4; ++j) { hre[j] = *(const f32x4*)(sre + 16 * j + 4 * q); him[j] = *(const f32x4*)(sim + 16 * j + 4 * q); }
;     const v2u xq = *(const v2u*)((const bf16*)(a.ws + WS_XB) + ((size_t)g * MP + row) * 16 + 4 * q), zq = *(const v2u*)((const bf16*)(a.ws + WS_ZB) + ((size_t)g * MP + row) * 16 + 4 * q);
.LBB0_963:
	s_and_b32 s28, s0, 63
	s_ashr_i32 s8, s0, 2
	v_and_or_b32 v80, s8, -16, v11
	s_lshl_b32 s8, s28, 9
	s_lshl_b32 s14, s28, 12
	s_mov_b32 s15, s9
	s_mov_b32 s27, s9
	s_mov_b32 s31, s9
	s_lshl_b32 s26, s28, 6
	s_lshl_b32 s30, s28, 7
	v_ashrrev_i32_e32 v81, 31, v80
	v_lshl_add_u64 v[64:65], v[4:5], 0, s[8:9]
	v_lshl_or_b32 v2, v10, 2, s14
	s_lshl_b32 s8, s28, 11
	s_mov_b32 s25, s9
	s_mul_i32 s24, s28, 0x2100
	v_lshl_add_u64 v[68:69], v[8:9], 0, s[14:15]
	v_lshl_add_u64 v[70:71], v[18:19], 0, s[26:27]
	v_lshl_add_u64 v[76:77], v[32:33], 0, s[30:31]
	v_lshl_add_u64 v[104:105], v[12:13], 0, v[2:3]
	v_lshl_add_u64 v[108:109], v[14:15], 0, v[2:3]
	v_lshl_add_u64 v[112:113], v[16:17], 0, s[8:9]
	v_lshl_add_u64 v[116:117], v[80:81], 0, s[10:11]
	global_load_dwordx4 v[36:39], v[64:65], off
	global_load_dwordx4 v[40:43], v[64:65], off offset:16
	global_load_dwordx4 v[44:47], v[64:65], off offset:128
	global_load_dwordx4 v[48:51], v[64:65], off offset:144
	global_load_dwordx4 v[52:55], v[64:65], off offset:256
	global_load_dwordx4 v[56:59], v[64:65], off offset:272
	global_load_dwordx4 v[60:63], v[64:65], off offset:384
	s_nop 0
	global_load_dwordx4 v[64:67], v[64:65], off offset:400
	s_nop 0
	global_load_dwordx2 v[144:145], v[68:69], off
	global_load_dwordx2 v[146:147], v[68:69], off offset:512
	global_load_dwordx2 v[148:149], v[68:69], off offset:1024
	global_load_dwordx2 v[150:151], v[68:69], off offset:1536
	global_load_dwordx2 v[152:153], v[68:69], off offset:2048
	global_load_dwordx2 v[154:155], v[68:69], off offset:2560
	global_load_dwordx2 v[156:157], v[68:69], off offset:3072
	global_load_dwordx2 v[158:159], v[68:69], off offset:3584
	s_nop 0
	global_load_dwordx4 v[68:71], v[70:71], off
	s_nop 0
	global_load_dwordx4 v[72:75], v[76:77], off
	s_nop 0
	global_load_dwordx4 v[76:79], v[76:77], off offset:64
	v_lshlrev_b64 v[114:115], 14, v[80:81]
	global_load_dwordx4 v[80:83], v[108:109], off
	global_load_dwordx4 v[84:87], v[104:105], off
	global_load_dwordx4 v[88:91], v[108:109], off offset:64
	global_load_dwordx4 v[92:95], v[104:105], off offset:64
	global_load_dwordx4 v[96:99], v[108:109], off offset:128
	global_load_dwordx4 v[100:103], v[104:105], off offset:128
	s_nop 0
	global_load_dwordx4 v[104:107], v[104:105], off offset:192
	s_nop 0
	global_load_dwordx4 v[108:111], v[108:109], off offset:192
	s_nop 0
	global_load_dword v2, v[112:113], off
	global_load_dword v163, v[112:113], off offset:64
	global_load_dword v182, v[112:113], off offset:128
	global_load_dword v183, v[112:113], off offset:192
	global_load_dword v184, v[112:113], off offset:256
	global_load_dword v185, v[112:113], off offset:320
	global_load_dword v186, v[112:113], off offset:384
	global_load_dword v187, v[112:113], off offset:448
	v_lshl_add_u64 v[112:113], v[116:117], 0, s[24:25]
	v_lshl_or_b32 v114, s28, 8, v114
	v_lshlrev_b64 v[160:161], 5, v[112:113]
	v_lshlrev_b64 v[116:117], 11, v[116:117]
	v_lshl_add_u64 v[132:133], v[20:21], 0, v[114:115]
	v_lshl_add_u64 v[140:141], v[22:23], 0, v[114:115]
	v_lshl_add_u64 v[170:171], v[24:25], 0, v[160:161]
	v_lshl_add_u64 v[160:161], v[26:27], 0, v[160:161]
	v_lshl_add_u64 v[164:165], v[28:29], 0, v[114:115]
	v_lshl_add_u64 v[166:167], v[30:31], 0, v[114:115]
	v_lshl_add_u64 v[168:169], s[94:95], 0, v[116:117]
	global_load_dwordx4 v[112:115], v[140:141], off
	global_load_dwordx4 v[116:119], v[132:133], off
	global_load_dwordx4 v[120:123], v[132:133], off offset:64
	global_load_dwordx4 v[124:127], v[140:141], off offset:64
	global_load_dwordx4 v[128:131], v[132:133], off offset:128
	s_nop 0
	global_load_dwordx4 v[132:135], v[132:133], off offset:192
	s_nop 0
	global_load_dwordx4 v[136:139], v[140:141], off offset:128
	s_nop 0
	global_load_dwordx4 v[140:143], v[140:141], off offset:192
	s_nop 0
	global_load_dwordx2 v[170:171], v[170:171], off
	s_nop 0
	global_load_dwordx2 v[160:161], v[160:161], off
	v_mov_b32_e32 v35, v3
	s_lshl_b32 s8, s28, 4
	v_lshl_add_u64 v[168:169], v[168:169], 0, s[8:9]
	s_add_i32 s0, s0, s1
	v_lshl_add_u64 v[168:169], v[168:169], 0, v[6:7]
	s_cmpk_lt_i32 s0, 0x200
	v_add_co_u32_e32 v168, vcc, 0x9800000, v168
	s_waitcnt vmcnt(44)
	v_mov_b32_e32 v174, v37
	s_waitcnt vmcnt(43)
	v_mov_b32_e32 v172, v41
	v_mov_b32_e32 v173, v43
	v_mov_b32_e32 v175, v39
	v_mov_b32_e32 v37, v38
	s_waitcnt vmcnt(42)
	v_mov_b32_e32 v176, v45
	v_mov_b32_e32 v177, v47
	v_mov_b32_e32 v45, v46
	s_waitcnt vmcnt(25)
	v_xor_b32_e32 v38, 0x80000000, v83
	v_xor_b32_e32 v39, 0x80000000, v82
	v_xor_b32_e32 v46, 0x80000000, v81
	v_xor_b32_e32 v47, 0x80000000, v80
	v_mov_b32_e32 v41, v42
	v_mov_b32_e32 v178, v53
	v_mov_b32_e32 v179, v55
	v_mov_b32_e32 v53, v54
	v_mov_b32_e32 v180, v61
	v_mov_b32_e32 v181, v63
	v_mov_b32_e32 v61, v62
	s_waitcnt vmcnt(23)
	v_xor_b32_e32 v54, 0x80000000, v91
	v_xor_b32_e32 v55, 0x80000000, v90
	v_xor_b32_e32 v62, 0x80000000, v89
	v_xor_b32_e32 v63, 0x80000000, v88
	v_cvt_pk_bf16_f32 v82, v47, v46
	v_cvt_pk_bf16_f32 v83, v39, v38
	s_waitcnt vmcnt(9)
	v_pk_mul_f32 v[38:39], v[172:173], v[114:115]
	v_pk_mul_f32 v[46:47], v[174:175], v[112:113]
	v_cvt_pk_bf16_f32 v80, v84, v85
	v_cvt_pk_bf16_f32 v81, v86, v87
	v_cvt_pk_bf16_f32 v85, v94, v95
	v_xor_b32_e32 v90, 0x80000000, v97
	v_xor_b32_e32 v91, 0x80000000, v96
	v_xor_b32_e32 v95, 0x80000000, v111
	v_xor_b32_e32 v96, 0x80000000, v110
	v_xor_b32_e32 v94, 0x80000000, v109
	v_xor_b32_e32 v97, 0x80000000, v108
	v_cvt_pk_bf16_f32 v86, v63, v62
	v_cvt_pk_bf16_f32 v87, v55, v54
	v_pk_mul_f32 v[54:55], v[40:41], v[114:115]
	v_pk_mul_f32 v[62:63], v[36:37], v[112:113]
	s_waitcnt vmcnt(8)
; #define MFMA16(A, B, Cc) __builtin_amdgcn_mfma_f32_16x16x32_bf16((A), (B), (Cc), 0, 0, 0)
; #define MFMA16K16(A, B, Cc) __builtin_amdgcn_mfma_f32_16x16x16bf16_1k(__builtin_bit_cast(bf16x4, (A)), __builtin_bit_cast(bf16x4, (B)), (Cc), 0, 0, 0)
; __device__ __forceinline__ unsigned pk2(float lo, float hi) { return pg8::cvt_pk_bf16(lo, hi); }
; __device__ __forceinline__ float bf_lo(unsigned w) { return __uint_as_float(w << 16); }
; __device__ __forceinline__ unsigned pk4f8(float a, float b, float c, float d) { int p = __builtin_amdgcn_cvt_pk_fp8_f32(sat8(a), sat8(b), 0, false); p = __builtin_amdgcn_cvt_pk_fp8_f32(sat8(c), sat8(d), p, true); return (unsigned)p; }
; __device__ __forceinline__ float bf_hi(unsigned w) { return __uint_as_float(w & 0xffff0000u); }
; __device__ __forceinline__ bf16x8 pack8(f32x4 lo, f32x4 hi) { v4u w; w.x = pk2(lo[0], lo[1]); w.y = pk2(lo[2], lo[3]); w.z = pk2(hi[0], hi[1]); w.w = pk2(hi[2], hi[3]); return __builtin_bit_cast(bf16x8, w); }
; __device__ __forceinline__ unsigned s5_output(const S5C& K, const f32x4 (&hre)[4], const f32x4 (&him)[4], v2u xq, v2u zq) {
;     f32x4 y = (f32x4){0.f, 0.f, 0.f, 0.f};
; #pragma unroll
;     for (int j = 0; j < 4; ++j) y = MFMA16(K.Cf[j], pack8(hre[j], him[j]), y);
;     const f32x4 xf = (f32x4){bf_lo(xq.x), bf_hi(xq.x), bf_lo(xq.y), bf_hi(xq.y)};
;     y = y + K.dsk * xf;
;     const v2u yb = (v2u){pk2(y[0], y[1]), pk2(y[2], y[3])};
;     const f32x4 gv = MFMA16K16(K.Wv, yb, K.bv), gg = MFMA16K16(K.Wg, yb, K.bg);
;     const f32x4 zf = (f32x4){bf_lo(zq.x), bf_hi(zq.x), bf_lo(zq.y), bf_hi(zq.y)};
;     f32x4 o;
; #pragma unroll
;     for (int r = 0; r < 4; ++r) o[r] = gv[r] * __builtin_amdgcn_rcpf(1.0f + __expf(-gg[r])) * zf[r];
;     return pk4f8(o[0], o[1], o[2], o[3]);
; __device__ __forceinline__ void s5_sample_task(const Args& a, int rb, int g, int lane) {
;     ...
;     S5_UPDATE(K, hre, him, xq);
;     float* ore = a.out + OUT_HSRE + ((size_t)i * NG + g) * PST; float* oim = a.out + OUT_HSIM + ((size_t)i * NG + g) * PST;
; #pragma unroll
;     for (int j = 0; j < 4; ++j) { *(f32x4*)(ore + 16 * j + 4 * q) = hre[j]; *(f32x4*)(oim + 16 * j + 4 * q) = him[j]; }
;     *(unsigned*)((unsigned char*)Y + row * DM + DA + g * 16 + 4 * q) = s5_output(K, hre, him, xq, zq);
	v_pk_fma_f32 v[38:39], v[40:41], v[118:119], v[38:39] neg_lo:[0,0,1] neg_hi:[0,0,1]
	v_pk_fma_f32 v[36:37], v[36:37], v[116:117], v[46:47] neg_lo:[0,0,1] neg_hi:[0,0,1]
	v_mov_b32_e32 v42, v49
	v_mov_b32_e32 v43, v51
	v_mov_b32_e32 v49, v50
	v_mov_b32_e32 v50, v57
	v_mov_b32_e32 v51, v59
	v_mov_b32_e32 v57, v58
	v_mov_b32_e32 v58, v65
	v_mov_b32_e32 v59, v67
	v_mov_b32_e32 v65, v66
	v_xor_b32_e32 v66, 0x80000000, v99
	v_xor_b32_e32 v67, 0x80000000, v98
	v_cvt_pk_bf16_f32 v94, v97, v94
	v_cvt_pk_bf16_f32 v95, v96, v95
	v_pk_fma_f32 v[40:41], v[172:173], v[118:119], v[54:55]
	s_waitcnt vmcnt(1)
	v_mfma_f32_16x16x16_bf16 v[96:99], v[144:145], v[170:171], v[36:39]
	v_cvt_pk_bf16_f32 v84, v92, v93
	v_cvt_pk_bf16_f32 v92, v104, v105
	v_cvt_pk_bf16_f32 v93, v106, v107
	v_pk_fma_f32 v[38:39], v[174:175], v[116:117], v[62:63]
	v_cvt_pk_bf16_f32 v90, v91, v90
	v_cvt_pk_bf16_f32 v91, v67, v66
	v_mfma_f32_16x16x16_bf16 v[36:39], v[146:147], v[170:171], v[38:41]
	v_mul_f32_e64 v66, v42, v126
	v_mul_f32_e64 v67, v43, v127
	v_pk_mul_f32 v[104:105], v[176:177], v[124:125]
	v_pk_mul_f32 v[106:107], v[48:49], v[126:127]
	v_pk_mul_f32 v[108:109], v[44:45], v[124:125]
	v_pk_mul_f32 v[110:111], v[50:51], v[138:139]
	v_pk_fma_f32 v[46:47], v[48:49], v[122:123], v[66:67] neg_lo:[0,0,1] neg_hi:[0,0,1]
	v_pk_fma_f32 v[44:45], v[44:45], v[120:121], v[104:105] neg_lo:[0,0,1] neg_hi:[0,0,1]
	v_pk_fma_f32 v[42:43], v[42:43], v[122:123], v[106:107]
	v_pk_fma_f32 v[40:41], v[176:177], v[120:121], v[108:109]
	v_pk_mul_f32 v[114:115], v[56:57], v[138:139]
	v_pk_fma_f32 v[48:49], v[56:57], v[130:131], v[110:111] neg_lo:[0,0,1] neg_hi:[0,0,1]
	v_mfma_f32_16x16x16_bf16 v[54:57], v[148:149], v[170:171], v[44:47]
	global_store_dwordx4 v[164:165], v[96:99], off sc1
	global_store_dwordx4 v[166:167], v[36:39], off sc1
	v_pk_mul_f32 v[112:113], v[178:179], v[136:137]
	v_cvt_pk_bf16_f32 v96, v96, v97
	v_mfma_f32_16x16x16_bf16 v[40:43], v[150:151], v[170:171], v[40:43]
	v_cvt_pk_bf16_f32 v97, v98, v99
	v_cvt_pk_bf16_f32 v98, v36, v37
	v_cvt_pk_bf16_f32 v99, v38, v39
	v_pk_mul_f32 v[124:125], v[52:53], v[136:137]
	v_pk_fma_f32 v[46:47], v[52:53], v[128:129], v[112:113] neg_lo:[0,0,1] neg_hi:[0,0,1]
	v_mfma_f32_16x16x32_bf16 v[80:83], v[80:83], v[96:99], 0
	v_fma_f32 v52, v50, v130, v114
	v_fma_f32 v53, v51, v131, v115
	v_pk_fma_f32 v[50:51], v[178:179], v[128:129], v[124:125]
	v_cvt_pk_bf16_f32 v88, v100, v101
	v_cvt_pk_bf16_f32 v89, v102, v103
	v_mfma_f32_16x16x16_bf16 v[44:47], v[152:153], v[170:171], v[46:49]
	v_cvt_pk_bf16_f32 v36, v54, v55
	v_cvt_pk_bf16_f32 v37, v56, v57
	v_cvt_pk_bf16_f32 v38, v40, v41
	v_mfma_f32_16x16x16_bf16 v[48:51], v[154:155], v[170:171], v[50:53]
	v_cvt_pk_bf16_f32 v39, v42, v43
	v_pk_mul_f32 v[126:127], v[58:59], v[142:143]
	v_pk_mul_f32 v[136:137], v[180:181], v[140:141]
	v_mfma_f32_16x16x32_bf16 v[36:39], v[84:87], v[36:39], v[80:83]
	v_mul_f32_e64 v138, v64, v142
	v_mul_f32_e64 v139, v65, v143
	v_pk_mul_f32 v[140:141], v[60:61], v[140:141]
	v_pk_fma_f32 v[62:63], v[64:65], v[134:135], v[126:127] neg_lo:[0,0,1] neg_hi:[0,0,1]
	v_pk_fma_f32 v[60:61], v[60:61], v[132:133], v[136:137] neg_lo:[0,0,1] neg_hi:[0,0,1]
	v_pk_fma_f32 v[66:67], v[58:59], v[134:135], v[138:139]
	v_pk_fma_f32 v[64:65], v[180:181], v[132:133], v[140:141]
	v_mfma_f32_16x16x16_bf16 v[58:61], v[156:157], v[170:171], v[60:63]
	v_cvt_pk_bf16_f32 v96, v44, v45
	v_cvt_pk_bf16_f32 v97, v46, v47
	v_cvt_pk_bf16_f32 v98, v48, v49
	v_mfma_f32_16x16x16_bf16 v[62:65], v[158:159], v[170:171], v[64:67]
	v_cvt_pk_bf16_f32 v99, v50, v51
	s_nop 2
	v_cvt_pk_bf16_f32 v80, v58, v59
	v_cvt_pk_bf16_f32 v81, v60, v61
	v_mfma_f32_16x16x32_bf16 v[36:39], v[88:91], v[96:99], v[36:39]
	v_cvt_pk_bf16_f32 v102, v163, v183
	v_cvt_pk_bf16_f32 v82, v62, v63
	v_cvt_pk_bf16_f32 v83, v64, v65
	v_cvt_pk_bf16_f32 v103, v185, v187
	v_lshlrev_b32_e32 v104, 16, v170
	v_mfma_f32_16x16x32_bf16 v[36:39], v[92:95], v[80:83], v[36:39]
	v_and_b32_e32 v105, 0xffff0000, v170
	v_lshlrev_b32_e32 v52, 16, v171
	v_and_b32_e32 v53, 0xffff0000, v171
	global_store_dwordx4 v[164:165], v[54:57], off offset:64 sc1
	global_store_dwordx4 v[166:167], v[40:43], off offset:64 sc1
	global_store_dwordx4 v[164:165], v[44:47], off offset:128 sc1
	s_nop 1
	v_pk_fma_f32 v[38:39], v[70:71], v[52:53], v[38:39]
	v_pk_fma_f32 v[36:37], v[68:69], v[104:105], v[36:37]
	v_cvt_pk_bf16_f32 v53, v38, v39
	v_cvt_pk_bf16_f32 v52, v36, v37
	v_cvt_pk_bf16_f32 v100, v2, v182
	v_cvt_pk_bf16_f32 v101, v184, v186
	v_mfma_f32_16x16x16_bf16 v[40:43], v[102:103], v[52:53], v[76:79]
	s_waitcnt vmcnt(5)
	v_lshlrev_b32_e32 v2, 16, v160
	v_and_b32_e32 v106, 0xffff0000, v160
	v_lshlrev_b32_e32 v107, 16, v161
	v_mfma_f32_16x16x16_bf16 v[36:39], v[100:101], v[52:53], v[72:75]
	v_and_b32_e32 v108, 0xffff0000, v161
	s_nop 1
	v_mul_f32_e32 v40, 0xbfb8aa3b, v40
	v_mul_f32_e32 v41, 0xbfb8aa3b, v41
	v_exp_f32_e32 v40, v40
	v_exp_f32_e32 v41, v41
	v_mul_f32_e32 v42, 0xbfb8aa3b, v42
	v_mul_f32_e32 v43, 0xbfb8aa3b, v43
	v_exp_f32_e32 v42, v42
	v_exp_f32_e32 v43, v43
	v_add_f32_e32 v40, 1.0, v40
	v_add_f32_e32 v41, 1.0, v41
	v_rcp_f32_e32 v40, v40
	v_rcp_f32_e32 v41, v41
	v_add_f32_e32 v42, 1.0, v42
	v_add_f32_e32 v43, 1.0, v43
	v_rcp_f32_e32 v42, v42
	v_rcp_f32_e32 v43, v43
	v_mul_f32_e32 v36, v36, v40
	v_mul_f32_e32 v37, v37, v41
	v_mul_f32_e32 v2, v36, v2
	v_mul_f32_e32 v36, v37, v106
	v_med3_f32 v2, v2, s2, v34
	v_med3_f32 v36, v36, s2, v34
	v_cvt_pk_fp8_f32 v35, v2, v36
	v_mul_f32_e32 v38, v38, v42
	v_mul_f32_e32 v39, v39, v43
	v_mul_f32_e32 v37, v38, v107
	v_mul_f32_e32 v2, v39, v108
	v_med3_f32 v36, v37, s2, v34
	v_med3_f32 v2, v2, s2, v34
	v_cvt_pk_fp8_f32 v35, v36, v2 op_sel:[0,0,1]
	v_addc_co_u32_e32 v169, vcc, 0, v169, vcc
	global_store_dwordx4 v[166:167], v[48:51], off offset:128 sc1
	global_store_dwordx4 v[164:165], v[58:61], off offset:192 sc1
	global_store_dwordx4 v[166:167], v[62:65], off offset:192 sc1
	global_store_dword v[168:169], v35, off offset:1024
	s_cbranch_scc1 .LBB0_963
